# v32 + differential-attention QK MFMAs in S0S0S1S1 S0S0S1S1 order instead of S0x4 S1x4
# baseline (speedup 1.0000x reference)
.LBB0_2781:
	s_add_i32 s46, s15, 1
	s_cmp_lt_u32 s15, 3
	s_cselect_b32 s48, s46, s15
	s_cselect_b32 s49, s38, s39
	s_lshl_b32 s48, s48, 6
	s_add_i32 s48, s48, s49
	s_ashr_i32 s49, s48, 31
	s_lshl_b64 s[50:51], s[48:49], 1
	s_add_u32 s50, s12, s50
	v_mad_i64_i32 v[2:3], s[48:49], s48, v242, v[132:133]
	s_addc_u32 s51, s13, s51
	s_add_i32 s48, s14, s6
	s_mov_b32 m0, s48
	s_nop 0
	global_load_lds_dwordx4 v[2:3], off
	s_add_i32 m0, s48, 0x2000
	v_lshl_add_u64 v[2:3], v[128:129], 1, s[50:51]
	global_load_lds_dwordx4 v[2:3], off
	v_lshl_add_u64 v[2:3], v[130:131], 1, s[50:51]
	s_add_i32 m0, s48, 0x4000
	s_mov_b32 s48, s7
	global_load_lds_dwordx4 v[2:3], off
	v_add_u32_e32 v0, s48, v137
	ds_read_b128 v[2:5], v0 offset:8192
	ds_read_b128 v[6:9], v0 offset:12288
	ds_read_b128 v[10:13], v0 offset:16384
	ds_read_b128 v[140:143], v0 offset:20480
	s_mov_b32 s7, s47
	v_exp_f32_e32 v14, v96
	v_exp_f32_e32 v144, v97
	v_exp_f32_e32 v98, v98
	v_exp_f32_e32 v146, v99
	v_exp_f32_e32 v15, v100
	v_exp_f32_e32 v145, v101
	v_exp_f32_e32 v99, v102
	v_exp_f32_e32 v147, v103
	v_add_u32_e32 v0, s48, v136
	v_pk_add_f32 v[96:97], v[14:15], v[144:145]
	v_pk_add_f32 v[100:101], v[98:99], v[146:147]
	s_nop 0
	v_pk_add_f32 v[96:97], v[96:97], v[100:101]
	v_cvt_pk_bf16_f32 v99, v99, v147
	v_pk_add_f32 v[156:157], v[96:97], v[96:97] op_sel_hi:[0,1]
	v_cvt_pk_bf16_f32 v96, v14, v144
	v_cvt_pk_bf16_f32 v97, v98, v146
	v_cvt_pk_bf16_f32 v98, v15, v145
	ds_read_b128 v[100:103], v0 offset:8192
	ds_read_b128 v[144:147], v0 offset:12288
	ds_read_b128 v[148:151], v0 offset:16384
	ds_read_b128 v[152:155], v0 offset:20480
	s_waitcnt lgkmcnt(0)
	v_mfma_f32_32x32x16_bf16 v[64:79], v[2:5], v[96:99], v[64:79]
	v_mfma_f32_32x32x16_bf16 v[48:63], v[6:9], v[96:99], v[48:63]
	v_mfma_f32_32x32x16_bf16 v[32:47], v[10:13], v[96:99], v[32:47]
	v_mfma_f32_32x32x16_bf16 v[16:31], v[140:143], v[96:99], v[16:31]
	v_exp_f32_e32 v2, v104
	v_exp_f32_e32 v4, v105
	v_exp_f32_e32 v3, v106
	v_exp_f32_e32 v5, v107
	v_exp_f32_e32 v6, v108
	v_exp_f32_e32 v8, v109
	v_exp_f32_e32 v7, v110
	v_exp_f32_e32 v9, v111
	v_pk_add_f32 v[10:11], v[2:3], v[4:5]
	v_add_u32_e32 v0, s48, v135
	v_pk_add_f32 v[14:15], v[10:11], v[10:11] op_sel_hi:[0,1]
	v_pk_add_f32 v[10:11], v[6:7], v[8:9]
	v_cvt_pk_bf16_f32 v2, v2, v4
	v_pk_add_f32 v[140:141], v[10:11], v[10:11] op_sel_hi:[0,1]
	v_cvt_pk_bf16_f32 v3, v3, v5
	v_cvt_pk_bf16_f32 v4, v6, v8
	v_cvt_pk_bf16_f32 v5, v7, v9
	ds_read_b128 v[6:9], v0 offset:8192
	ds_read_b128 v[10:13], v0 offset:12288
	ds_read_b128 v[96:99], v0 offset:16384
	ds_read_b128 v[104:107], v0 offset:20480
	v_mfma_f32_32x32x16_bf16 v[64:79], v[100:103], v[2:5], v[64:79]
	v_mfma_f32_32x32x16_bf16 v[48:63], v[144:147], v[2:5], v[48:63]
	v_mfma_f32_32x32x16_bf16 v[32:47], v[148:151], v[2:5], v[32:47]
	v_mfma_f32_32x32x16_bf16 v[16:31], v[152:155], v[2:5], v[16:31]
	v_exp_f32_e32 v0, v80
	v_exp_f32_e32 v2, v81
	v_exp_f32_e32 v3, v82
	v_exp_f32_e32 v4, v83
	v_exp_f32_e32 v5, v84
	v_exp_f32_e32 v14, v85
	v_exp_f32_e32 v80, v86
	v_exp_f32_e32 v81, v87
	v_add_f32_e32 v143, v0, v2
	v_cvt_pk_bf16_f32 v2, v0, v2
	v_add_u32_e32 v0, s48, v134
	v_add_f32_e32 v145, v3, v4
	v_add_f32_e32 v147, v5, v14
	v_add_f32_e32 v149, v80, v81
	v_cvt_pk_bf16_f32 v3, v3, v4
	v_cvt_pk_bf16_f32 v4, v5, v14
	v_cvt_pk_bf16_f32 v5, v80, v81
	ds_read_b128 v[80:83], v0 offset:8192
	ds_read_b128 v[84:87], v0 offset:12288
	ds_read_b128 v[100:103], v0 offset:16384
	ds_read_b128 v[108:111], v0 offset:20480
	s_waitcnt lgkmcnt(0)
	v_mfma_f32_32x32x16_bf16 v[64:79], v[6:9], v[2:5], v[64:79]
	v_mfma_f32_32x32x16_bf16 v[48:63], v[10:13], v[2:5], v[48:63]
	v_mfma_f32_32x32x16_bf16 v[32:47], v[96:99], v[2:5], v[32:47]
	v_mfma_f32_32x32x16_bf16 v[16:31], v[104:107], v[2:5], v[16:31]
	v_exp_f32_e32 v142, v88
	v_exp_f32_e32 v144, v89
	v_exp_f32_e32 v146, v90
	v_exp_f32_e32 v148, v91
	v_exp_f32_e32 v14, v92
	v_exp_f32_e32 v140, v93
	v_exp_f32_e32 v156, v94
	v_exp_f32_e32 v0, v95
	v_cvt_pk_bf16_f32 v2, v142, v144
	v_cvt_pk_bf16_f32 v3, v146, v148
	v_cvt_pk_bf16_f32 v4, v14, v140
	v_cvt_pk_bf16_f32 v5, v156, v0
	s_nop 1
	v_mfma_f32_32x32x16_bf16 v[64:79], v[80:83], v[2:5], v[64:79]
	v_add_f32_e64 v6, v142, v144
	v_add_f32_e64 v7, v143, v145
	v_add_f32_e64 v8, v146, v148
	v_add_f32_e64 v9, v147, v149
	v_add_f32_e64 v10, v156, v0
	v_add_f32_e64 v11, v157, v1
	v_pk_add_f32 v[6:7], v[6:7], v[8:9]
	v_pk_add_f32 v[8:9], v[14:15], v[140:141]
	s_nop 0
	v_pk_add_f32 v[8:9], v[8:9], v[10:11]
	v_mfma_f32_32x32x16_bf16 v[48:63], v[84:87], v[2:5], v[48:63]
	v_add_f32_e64 v6, v6, v8
	v_add_f32_e64 v7, v7, v9
	v_pk_add_f32 v[6:7], v[6:7], v[6:7] op_sel:[0,1] op_sel_hi:[1,0]
	v_mfma_f32_32x32x16_bf16 v[32:47], v[100:103], v[2:5], v[32:47]
	v_mfma_f32_32x32x16_bf16 v[16:31], v[108:111], v[2:5], v[16:31]
	v_mov_b32_e32 v0, v6
	s_nop 1
	v_permlane32_swap_b32_e32 v6, v0
	v_add_f32_e32 v0, v6, v0
	v_add_f32_e32 v139, v139, v0
	v_add_u32_e32 v0, s7, v137
	ds_read_b128 v[2:5], v0
	ds_read_b128 v[6:9], v0 offset:4096
	v_add_u32_e32 v0, s7, v136
	ds_read_b128 v[10:13], v0
	ds_read_b128 v[140:143], v0 offset:4096
	v_add_u32_e32 v0, s7, v135
	v_add_u32_e32 v14, s7, v134
	ds_read_b128 v[144:147], v0
	ds_read_b128 v[148:151], v0 offset:4096
	ds_read_b128 v[152:155], v14
	ds_read_b128 v[156:159], v14 offset:4096
	v_xor_b32_e32 v80, 0x80000000, v138
	v_mov_b32_e32 v81, v80
	v_mov_b32_e32 v82, v80
	v_mov_b32_e32 v83, v80
	v_mov_b32_e32 v84, v80
	v_mov_b32_e32 v85, v80
	v_mov_b32_e32 v86, v80
	v_mov_b32_e32 v87, v80
	v_mov_b32_e32 v88, v80
	v_mov_b32_e32 v89, v80
	v_mov_b32_e32 v90, v80
	v_mov_b32_e32 v91, v80
	v_mov_b32_e32 v92, v80
	v_mov_b32_e32 v93, v80
	v_mov_b32_e32 v94, v80
	v_mov_b32_e32 v95, v80
	s_waitcnt lgkmcnt(0)
	s_nop 0
	v_mfma_f32_32x32x16_bf16 v[96:111], v[2:5], v[124:127], v[80:95]
	v_mfma_f32_32x32x16_bf16 v[96:111], v[10:13], v[120:123], v[96:111]
	v_mfma_f32_32x32x16_bf16 v[80:95], v[6:9], v[124:127], v[80:95]
	v_mfma_f32_32x32x16_bf16 v[80:95], v[140:143], v[120:123], v[80:95]
	v_mfma_f32_32x32x16_bf16 v[96:111], v[144:147], v[116:119], v[96:111]
	v_mfma_f32_32x32x16_bf16 v[96:111], v[152:155], v[112:115], v[96:111]
	v_mfma_f32_32x32x16_bf16 v[80:95], v[148:151], v[116:119], v[80:95]
	s_nop 10
	v_max_f32_e32 v0, v97, v97
	v_max_f32_e32 v2, v96, v96
	v_max_f32_e32 v0, v2, v0
	v_max3_f32 v0, v0, v98, v99
	v_max3_f32 v0, v0, v100, v101
	v_max3_f32 v0, v0, v102, v103
	v_max3_f32 v0, v0, v104, v105
	v_mfma_f32_32x32x16_bf16 v[80:95], v[156:159], v[112:115], v[80:95]
	v_max3_f32 v0, v0, v106, v107
	v_max3_f32 v0, v0, v108, v109
	v_max3_f32 v0, v0, v110, v111
	s_mov_b32 s47, 0x41000000
	s_nop 11
	v_max3_f32 v0, v0, v80, v81
	v_max3_f32 v0, v0, v82, v83
	v_max3_f32 v0, v0, v84, v85
	v_max3_f32 v0, v0, v86, v87
	v_max3_f32 v0, v0, v88, v89
	v_max3_f32 v0, v0, v90, v91
	v_max3_f32 v0, v0, v92, v93
	v_max3_f32 v0, v0, v94, v95
	v_mov_b32_e32 v2, v0
	s_nop 1
	v_permlane32_swap_b32_e32 v0, v2
	v_max_f32_e32 v2, v2, v2
	v_max_f32_e32 v0, v0, v0
	v_max_f32_e32 v0, v0, v2
	v_cmp_ge_f32_e32 vcc, s47, v0
	s_cmp_eq_u64 vcc, exec
	s_cbranch_scc1 .LBB0_2783
	v_max_f32_e32 v0, v0, v0
	v_max_f32_e32 v2, 0, v0
	v_exp_f32_e64 v0, -v2
	v_add_f32_e32 v138, v138, v2
	v_sub_f32_e32 v111, v111, v2
	v_sub_f32_e32 v110, v110, v2
	v_pk_mul_f32 v[78:79], v[78:79], v[0:1] op_sel_hi:[1,0]
	v_pk_mul_f32 v[76:77], v[76:77], v[0:1] op_sel_hi:[1,0]
	v_pk_mul_f32 v[74:75], v[74:75], v[0:1] op_sel_hi:[1,0]
	v_pk_mul_f32 v[72:73], v[72:73], v[0:1] op_sel_hi:[1,0]
	v_pk_mul_f32 v[70:71], v[70:71], v[0:1] op_sel_hi:[1,0]
	v_pk_mul_f32 v[68:69], v[68:69], v[0:1] op_sel_hi:[1,0]
	v_pk_mul_f32 v[66:67], v[66:67], v[0:1] op_sel_hi:[1,0]
	v_pk_mul_f32 v[64:65], v[64:65], v[0:1] op_sel_hi:[1,0]
	v_pk_mul_f32 v[62:63], v[62:63], v[0:1] op_sel_hi:[1,0]
	v_pk_mul_f32 v[60:61], v[60:61], v[0:1] op_sel_hi:[1,0]
	v_pk_mul_f32 v[58:59], v[58:59], v[0:1] op_sel_hi:[1,0]
	v_pk_mul_f32 v[56:57], v[56:57], v[0:1] op_sel_hi:[1,0]
	v_pk_mul_f32 v[54:55], v[54:55], v[0:1] op_sel_hi:[1,0]
	v_pk_mul_f32 v[52:53], v[52:53], v[0:1] op_sel_hi:[1,0]
	v_pk_mul_f32 v[50:51], v[50:51], v[0:1] op_sel_hi:[1,0]
	v_pk_mul_f32 v[48:49], v[48:49], v[0:1] op_sel_hi:[1,0]
	v_pk_mul_f32 v[46:47], v[46:47], v[0:1] op_sel_hi:[1,0]
	v_pk_mul_f32 v[44:45], v[44:45], v[0:1] op_sel_hi:[1,0]
	v_pk_mul_f32 v[42:43], v[42:43], v[0:1] op_sel_hi:[1,0]
	v_pk_mul_f32 v[40:41], v[40:41], v[0:1] op_sel_hi:[1,0]
	v_pk_mul_f32 v[38:39], v[38:39], v[0:1] op_sel_hi:[1,0]
	v_pk_mul_f32 v[36:37], v[36:37], v[0:1] op_sel_hi:[1,0]
	v_pk_mul_f32 v[34:35], v[34:35], v[0:1] op_sel_hi:[1,0]
	v_pk_mul_f32 v[32:33], v[32:33], v[0:1] op_sel_hi:[1,0]
	v_pk_mul_f32 v[30:31], v[30:31], v[0:1] op_sel_hi:[1,0]
	v_pk_mul_f32 v[28:29], v[28:29], v[0:1] op_sel_hi:[1,0]
	v_pk_mul_f32 v[26:27], v[26:27], v[0:1] op_sel_hi:[1,0]
	v_pk_mul_f32 v[24:25], v[24:25], v[0:1] op_sel_hi:[1,0]
	v_pk_mul_f32 v[22:23], v[22:23], v[0:1] op_sel_hi:[1,0]
	v_pk_mul_f32 v[20:21], v[20:21], v[0:1] op_sel_hi:[1,0]
	v_pk_mul_f32 v[18:19], v[18:19], v[0:1] op_sel_hi:[1,0]
	v_pk_mul_f32 v[16:17], v[16:17], v[0:1] op_sel_hi:[1,0]
	v_sub_f32_e32 v109, v109, v2
	v_sub_f32_e32 v108, v108, v2
	v_sub_f32_e32 v107, v107, v2
	v_sub_f32_e32 v106, v106, v2
	v_sub_f32_e32 v105, v105, v2
	v_sub_f32_e32 v104, v104, v2
	v_sub_f32_e32 v103, v103, v2
	v_sub_f32_e32 v102, v102, v2
	v_sub_f32_e32 v101, v101, v2
	v_sub_f32_e32 v100, v100, v2
	v_sub_f32_e32 v99, v99, v2
	v_sub_f32_e32 v98, v98, v2
	v_sub_f32_e32 v97, v97, v2
	v_sub_f32_e32 v96, v96, v2
	v_sub_f32_e32 v95, v95, v2
	v_sub_f32_e32 v94, v94, v2
	v_sub_f32_e32 v93, v93, v2
	v_sub_f32_e32 v92, v92, v2
	v_sub_f32_e32 v91, v91, v2
	v_sub_f32_e32 v90, v90, v2
	v_sub_f32_e32 v89, v89, v2
	v_sub_f32_e32 v88, v88, v2
	v_sub_f32_e32 v87, v87, v2
	v_sub_f32_e32 v86, v86, v2
	v_sub_f32_e32 v85, v85, v2
	v_sub_f32_e32 v84, v84, v2
	v_sub_f32_e32 v83, v83, v2
	v_sub_f32_e32 v82, v82, v2
	v_sub_f32_e32 v81, v81, v2
	v_sub_f32_e32 v80, v80, v2
	v_mul_f32_e32 v139, v139, v0
